# NA tile: QK operands read 8 MFMAs ahead (extra K buffers in dead registers), counted waits
# baseline (speedup 1.0000x reference)
; template <bool DIFF>
; __device__ __forceinline__ void qkt(f32x16& a, f32x16& b, const char* Ks, const char* Qs, int krow, int r32, int hi) {
;   a = f32x16{}; b = f32x16{};
; #pragma unroll
;   for (int d = 0; d < 4; ++d) {
;     const int cb0 = (d * 16 + hi * 8) * 2, cb1 = ((d + 4) * 16 + hi * 8) * 2;
;     const bf16x8 k0 = *reinterpret_cast<const bf16x8*>(Ks + KSWZ(krow, cb0)), q0 = *reinterpret_cast<const bf16x8*>(Qs + KSWZ(r32, cb0));
;     const bf16x8 k1 = *reinterpret_cast<const bf16x8*>(Ks + KSWZ(krow, cb1)), q1 = *reinterpret_cast<const bf16x8*>(Qs + KSWZ(r32, cb1));
;     a = __builtin_amdgcn_mfma_f32_32x32x16_bf16(k0, q0, a, 0, 0, 0);
;     b = __builtin_amdgcn_mfma_f32_32x32x16_bf16(k1, q1, b, 0, 0, 0); }
;   if (!DIFF) {
; #pragma unroll
;     for (int r = 0; r < 16; ++r) a[r] += b[r]; }
.LBB0_369:
	v_cmp_ge_u32_e32 vcc, s40, v159
	v_cmp_lt_u32_e64 s[40:41], s40, v160
	s_and_b64 s[88:89], vcc, s[40:41]
	s_and_saveexec_b64 s[40:41], s[88:89]
	s_cbranch_execz .LBB0_439
	v_add_u32_e32 v78, v161, v162
	v_add_u32_e32 v79, v161, v163
	v_add_u32_e32 v153, v161, v164
	v_add_u32_e32 v185, v161, v165
	v_add_u32_e32 v206, v161, v166
	v_add_u32_e32 v207, v161, v167
	v_add_u32_e32 v209, v161, v168
	v_add_u32_e32 v222, v161, v169
	ds_read_b128 v[224:227], v78
	ds_read_b128 v[70:73], v175 offset:36864
	ds_read_b128 v[228:231], v79
	ds_read_b128 v[82:85], v176 offset:36864
	ds_read_b128 v[232:235], v153
	ds_read_b128 v[186:189], v177 offset:36864
	ds_read_b128 v[236:239], v185
	ds_read_b128 v[190:193], v178 offset:36864
	ds_read_b128 v[240:243], v206
	ds_read_b128 v[194:197], v179 offset:36864
	ds_read_b128 v[244:247], v207
	ds_read_b128 v[198:201], v180 offset:36864
	ds_read_b128 v[248:251], v209
	ds_read_b128 v[202:205], v181 offset:36864
	ds_read_b128 v[214:217], v222
	ds_read_b128 v[210:213], v182 offset:36864
	s_waitcnt lgkmcnt(14)
	v_mfma_f32_32x32x16_bf16 v[98:113], v[224:227], v[70:73], 0
	ds_read_b128 v[224:227], v78 offset:8192
	s_waitcnt lgkmcnt(13)
	v_mfma_f32_32x32x16_bf16 v[114:129], v[228:231], v[82:85], 0
	ds_read_b128 v[228:231], v79 offset:8192
	s_waitcnt lgkmcnt(12)
	v_mfma_f32_32x32x16_bf16 v[98:113], v[232:235], v[186:189], v[98:113]
	ds_read_b128 v[232:235], v153 offset:8192
	s_waitcnt lgkmcnt(11)
	v_mfma_f32_32x32x16_bf16 v[114:129], v[236:239], v[190:193], v[114:129]
	ds_read_b128 v[236:239], v185 offset:8192
	s_waitcnt lgkmcnt(10)
	v_mfma_f32_32x32x16_bf16 v[98:113], v[240:243], v[194:197], v[98:113]
	ds_read_b128 v[240:243], v206 offset:8192
	s_waitcnt lgkmcnt(9)
	v_mfma_f32_32x32x16_bf16 v[114:129], v[244:247], v[198:201], v[114:129]
	ds_read_b128 v[244:247], v207 offset:8192
	s_waitcnt lgkmcnt(8)
	v_mfma_f32_32x32x16_bf16 v[98:113], v[248:251], v[202:205], v[98:113]
	ds_read_b128 v[248:251], v209 offset:8192
	s_waitcnt lgkmcnt(7)
	v_mfma_f32_32x32x16_bf16 v[114:129], v[214:217], v[210:213], v[114:129]
	ds_read_b128 v[214:217], v222 offset:8192
	s_waitcnt lgkmcnt(7)
	v_mfma_f32_32x32x16_bf16 v[66:81], v[224:227], v[70:73], 0
	s_waitcnt lgkmcnt(6)
	v_mfma_f32_32x32x16_bf16 v[82:97], v[228:231], v[82:85], 0
	s_waitcnt lgkmcnt(5)
	v_mfma_f32_32x32x16_bf16 v[66:81], v[232:235], v[186:189], v[66:81]
	s_waitcnt lgkmcnt(4)
	v_mfma_f32_32x32x16_bf16 v[82:97], v[236:239], v[190:193], v[82:97]
	s_waitcnt lgkmcnt(3)
	v_mfma_f32_32x32x16_bf16 v[66:81], v[240:243], v[194:197], v[66:81]
	s_waitcnt lgkmcnt(2)
	v_mfma_f32_32x32x16_bf16 v[82:97], v[244:247], v[198:201], v[82:97]
	s_waitcnt lgkmcnt(1)
	v_mfma_f32_32x32x16_bf16 v[66:81], v[248:251], v[202:205], v[66:81]
	s_waitcnt lgkmcnt(0)
	v_mfma_f32_32x32x16_bf16 v[82:97], v[214:217], v[210:213], v[82:97]
	ds_read_b32 v223, v170
	ds_read_b32 v224, v170 offset:4
	ds_read_b32 v225, v170 offset:8
	ds_read_b32 v226, v170 offset:12
	ds_read_b32 v227, v170 offset:32
	ds_read_b32 v228, v170 offset:36
	ds_read_b32 v229, v170 offset:40
	ds_read_b32 v230, v170 offset:44
	ds_read_b32 v231, v170 offset:64
	ds_read_b32 v232, v170 offset:68
	ds_read_b32 v233, v170 offset:72
	ds_read_b32 v234, v170 offset:76
	ds_read_b32 v235, v170 offset:96
	ds_read_b32 v236, v170 offset:100
	ds_read_b32 v237, v170 offset:104
	ds_read_b32 v238, v170 offset:108
	ds_read_b32 v239, v170 offset:128
	ds_read_b32 v240, v170 offset:132
	ds_read_b32 v241, v170 offset:136
	ds_read_b32 v242, v170 offset:140
	ds_read_b32 v243, v170 offset:160
	ds_read_b32 v244, v170 offset:164
	ds_read_b32 v245, v170 offset:168
	ds_read_b32 v246, v170 offset:172
	ds_read_b32 v247, v170 offset:192
	ds_read_b32 v248, v170 offset:196
	ds_read_b32 v249, v170 offset:200
	ds_read_b32 v250, v170 offset:204
	ds_read_b32 v251, v170 offset:224
	ds_read_b32 v252, v170 offset:228
	ds_read_b32 v253, v170 offset:232
	ds_read_b32 v254, v170 offset:236
	v_mov_b32_e32 v153, 0xf149f2ca
	v_mov_b32_e32 v185, 0xf149f2ca
	v_add_f32_e32 v98, v98, v114
	s_waitcnt lgkmcnt(15)
	v_add_f32_e32 v98, v98, v223
	v_cndmask_b32_e64 v185, v185, v98, s[4:5]
	v_add_f32_e32 v98, v99, v115
	s_waitcnt lgkmcnt(15)
	v_add_f32_e32 v98, v98, v224
	v_cndmask_b32_e64 v153, v153, v98, s[6:7]
	v_mov_b32_e32 v98, 0xf149f2ca
	v_mov_b32_e32 v99, 0xf149f2ca
	v_add_f32_e32 v100, v100, v116
	s_waitcnt lgkmcnt(15)
	v_add_f32_e32 v100, v100, v225
	v_cndmask_b32_e64 v99, v99, v100, s[8:9]
	v_add_f32_e32 v100, v101, v117
	s_waitcnt lgkmcnt(15)
	v_add_f32_e32 v100, v100, v226
	v_cndmask_b32_e64 v98, v98, v100, s[10:11]
	v_mov_b32_e32 v100, 0xf149f2ca
	v_mov_b32_e32 v101, 0xf149f2ca
	v_add_f32_e32 v102, v102, v118
	s_waitcnt lgkmcnt(15)
	v_add_f32_e32 v102, v102, v227
	v_cndmask_b32_e64 v101, v101, v102, s[12:13]
	v_add_f32_e32 v102, v103, v119
	s_waitcnt lgkmcnt(15)
	v_add_f32_e32 v102, v102, v228
	v_cndmask_b32_e64 v100, v100, v102, s[14:15]
	v_mov_b32_e32 v102, 0xf149f2ca
	v_mov_b32_e32 v103, 0xf149f2ca
	v_add_f32_e32 v104, v104, v120
	s_waitcnt lgkmcnt(15)
	v_add_f32_e32 v104, v104, v229
	v_cndmask_b32_e64 v103, v103, v104, s[16:17]
	v_add_f32_e32 v104, v105, v121
	s_waitcnt lgkmcnt(15)
; __device__ __forceinline__ int crow(int r, int hi) { return (r & 3) + 8 * (r >> 2) + 4 * hi; }
; template <bool DIFF> ...
;     ...
;         float mx = a0[0];
; #pragma unroll
;         for (int r = 1; r < 16; ++r) mx = fmaxf(mx, a0[r]);
; #pragma unroll
;         for (int r = 0; r < 16; ++r) mx = fmaxf(mx, a1[r]);
;         { auto rr = __builtin_amdgcn_permlane32_swap(__float_as_uint(mx), __float_as_uint(mx), false, false); mx = fmaxf(__uint_as_float(rr[0]), __uint_as_float(rr[1])); }
;         const float mn = fmaxf(m1, mx), alpha = __builtin_amdgcn_exp2f((m1 - mn) * C), x1 = -mn * C; m1 = mn;
;         float ps = 0.f;
; #pragma unroll
;         for (int r = 0; r < 16; ++r) { a0[r] = __builtin_amdgcn_exp2f(fmaf(a0[r], C, x1)); ps += a0[r]; }
; #pragma unroll
;         for (int r = 0; r < 16; ++r) { a1[r] = __builtin_amdgcn_exp2f(fmaf(a1[r], C, x1)); ps += a1[r]; }
;         l1 = l1 * alpha + ps;
;         if (__any(alpha < 1.0f)) {
;           if (hi == 0) wsc[r32] = alpha;
;           asm volatile("s_waitcnt lgkmcnt(0)" ::: "memory");
; #pragma unroll
;           for (int r = 0; r < 16; ++r) { const float al = wsc[crow(r, hi)];
	v_add_f32_e32 v104, v104, v230
	v_cndmask_b32_e64 v102, v102, v104, s[18:19]
	v_mov_b32_e32 v104, 0xf149f2ca
	v_mov_b32_e32 v105, 0xf149f2ca
	v_add_f32_e32 v106, v106, v122
	s_waitcnt lgkmcnt(15)
	v_add_f32_e32 v106, v106, v231
	v_cndmask_b32_e64 v105, v105, v106, s[54:55]
	v_add_f32_e32 v106, v107, v123
	s_waitcnt lgkmcnt(15)
	v_add_f32_e32 v106, v106, v232
	v_cndmask_b32_e64 v104, v104, v106, s[56:57]
	v_mov_b32_e32 v106, 0xf149f2ca
	v_mov_b32_e32 v107, 0xf149f2ca
	v_add_f32_e32 v108, v108, v124
	s_waitcnt lgkmcnt(15)
	v_add_f32_e32 v108, v108, v233
	v_cndmask_b32_e64 v107, v107, v108, s[58:59]
	v_add_f32_e32 v108, v109, v125
	s_waitcnt lgkmcnt(15)
	v_add_f32_e32 v108, v108, v234
	v_cndmask_b32_e64 v106, v106, v108, s[60:61]
	v_mov_b32_e32 v108, 0xf149f2ca
	v_mov_b32_e32 v109, 0xf149f2ca
	v_add_f32_e32 v110, v110, v126
	s_waitcnt lgkmcnt(15)
	v_add_f32_e32 v110, v110, v235
	v_cndmask_b32_e64 v109, v109, v110, s[62:63]
	v_add_f32_e32 v110, v111, v127
	s_waitcnt lgkmcnt(15)
	v_add_f32_e32 v110, v110, v236
	v_cndmask_b32_e64 v108, v108, v110, s[64:65]
	v_mov_b32_e32 v110, 0xf149f2ca
	v_mov_b32_e32 v111, 0xf149f2ca
	v_add_f32_e32 v112, v112, v128
	s_waitcnt lgkmcnt(15)
	v_add_f32_e32 v112, v112, v237
	v_cndmask_b32_e64 v111, v111, v112, s[66:67]
	v_add_f32_e32 v112, v113, v129
	s_waitcnt lgkmcnt(15)
	v_add_f32_e32 v112, v112, v238
	v_cndmask_b32_e64 v110, v110, v112, s[68:69]
	v_mov_b32_e32 v112, 0xf149f2ca
	v_mov_b32_e32 v113, 0xf149f2ca
	v_add_f32_e32 v66, v66, v82
	s_waitcnt lgkmcnt(15)
	v_add_f32_e32 v66, v66, v239
	v_cndmask_b32_e64 v113, v113, v66, s[70:71]
	v_add_f32_e32 v66, v67, v83
	s_waitcnt lgkmcnt(14)
	v_add_f32_e32 v66, v66, v240
	v_cndmask_b32_e64 v112, v112, v66, s[72:73]
	v_mov_b32_e32 v66, 0xf149f2ca
	v_mov_b32_e32 v67, 0xf149f2ca
	v_add_f32_e32 v68, v68, v84
	s_waitcnt lgkmcnt(13)
	v_add_f32_e32 v68, v68, v241
	v_cndmask_b32_e64 v67, v67, v68, s[74:75]
	v_add_f32_e32 v68, v69, v85
	s_waitcnt lgkmcnt(12)
	v_add_f32_e32 v68, v68, v242
	v_cndmask_b32_e64 v66, v66, v68, s[76:77]
	v_mov_b32_e32 v69, 0xf149f2ca
	v_mov_b32_e32 v82, 0xf149f2ca
	v_add_f32_e32 v68, v70, v86
	s_waitcnt lgkmcnt(11)
	v_add_f32_e32 v68, v68, v243
	v_cndmask_b32_e64 v82, v82, v68, s[78:79]
	v_add_f32_e32 v68, v71, v87
	s_waitcnt lgkmcnt(10)
	v_add_f32_e32 v68, v68, v244
	v_cndmask_b32_e64 v69, v69, v68, s[80:81]
	v_mov_b32_e32 v70, 0xf149f2ca
	v_mov_b32_e32 v71, 0xf149f2ca
	v_add_f32_e32 v68, v72, v88
	s_waitcnt lgkmcnt(9)
	v_add_f32_e32 v68, v68, v245
	v_cndmask_b32_e64 v71, v71, v68, s[82:83]
	v_add_f32_e32 v68, v73, v89
	s_waitcnt lgkmcnt(8)
	v_add_f32_e32 v68, v68, v246
	v_cndmask_b32_e64 v70, v70, v68, s[84:85]
	v_mov_b32_e32 v72, 0xf149f2ca
	v_mov_b32_e32 v73, 0xf149f2ca
	v_add_f32_e32 v68, v74, v90
	s_waitcnt lgkmcnt(7)
	v_add_f32_e32 v68, v68, v247
	v_cndmask_b32_e64 v73, v73, v68, s[20:21]
	v_add_f32_e32 v68, v75, v91
	s_waitcnt lgkmcnt(6)
	v_add_f32_e32 v68, v68, v248
	v_cndmask_b32_e64 v72, v72, v68, s[22:23]
	v_mov_b32_e32 v74, 0xf149f2ca
	v_mov_b32_e32 v75, 0xf149f2ca
	v_add_f32_e32 v68, v76, v92
	s_waitcnt lgkmcnt(5)
	v_add_f32_e32 v68, v68, v249
	v_cndmask_b32_e64 v75, v75, v68, s[24:25]
	v_add_f32_e32 v68, v77, v93
	s_waitcnt lgkmcnt(4)
	v_add_f32_e32 v68, v68, v250
	v_cndmask_b32_e64 v74, v74, v68, s[26:27]
	v_mov_b32_e32 v76, 0xf149f2ca
	v_mov_b32_e32 v77, 0xf149f2ca
	v_add_f32_e32 v68, v78, v94
	s_waitcnt lgkmcnt(3)
	v_add_f32_e32 v68, v68, v251
	v_cndmask_b32_e64 v77, v77, v68, s[28:29]
	v_add_f32_e32 v68, v79, v95
	s_waitcnt lgkmcnt(2)
	v_add_f32_e32 v68, v68, v252
	v_cndmask_b32_e64 v76, v76, v68, s[30:31]
	v_mov_b32_e32 v78, 0xf149f2ca
	v_mov_b32_e32 v79, 0xf149f2ca
	v_add_f32_e32 v68, v80, v96
	s_waitcnt lgkmcnt(1)
	v_add_f32_e32 v68, v68, v253
	v_cndmask_b32_e64 v79, v79, v68, s[34:35]
	v_add_f32_e32 v68, v81, v97
	s_waitcnt lgkmcnt(0)
	v_add_f32_e32 v68, v68, v254
	v_cndmask_b32_e64 v78, v78, v68, s[36:37]
	v_max_f32_e32 v68, v153, v153
	v_max_f32_e32 v80, v185, v185
	v_max_f32_e32 v68, v80, v68
	v_max3_f32 v68, v68, v99, v98
	v_max3_f32 v68, v68, v101, v100
	v_max3_f32 v68, v68, v103, v102
	v_max3_f32 v68, v68, v105, v104
	v_max3_f32 v68, v68, v107, v106
	v_max3_f32 v68, v68, v109, v108
	v_max3_f32 v68, v68, v111, v110
	v_max3_f32 v68, v68, v113, v112
	v_max3_f32 v68, v68, v67, v66
	v_max3_f32 v68, v68, v82, v69
	v_max3_f32 v68, v68, v71, v70
	v_max3_f32 v68, v68, v73, v72
	v_max3_f32 v68, v68, v75, v74
	v_max3_f32 v68, v68, v77, v76
	v_max3_f32 v68, v68, v79, v78
	v_mov_b32_e32 v80, v68
	s_nop 1
	v_permlane32_swap_b32_e32 v68, v80
	v_max3_f32 v68, v184, v68, v80
	v_sub_f32_e32 v80, v184, v68
	v_mul_f32_e32 v80, 0x3e0293ee, v80
	v_exp_f32_e32 v80, v80
	s_nop 0
	v_cmp_gt_f32_e32 vcc, 1.0, v80
	s_mov_b32 s32, 0
	s_cbranch_vccz .LBB0_438
	s_mov_b32 s32, 1
	s_and_saveexec_b64 s[88:89], s[38:39]
	ds_write_b32 v157, v80 offset:34816
	s_or_b64 exec, exec, s[88:89]
	s_waitcnt lgkmcnt(0)
	v_add_u32_e32 v81, v156, v0
	ds_read_b128 v[118:121], v81 offset:34912
	ds_read_b128 v[122:125], v81 offset:34880
	ds_read_b128 v[126:129], v81 offset:34848
	ds_read_b128 v[114:117], v81 offset:34816
